# weight convert+transpose loops: the four row loads per thread issued together (extra register groups), barrier after the loads
# speedup vs baseline: 1.0209x; 1.0015x over previous
.LBB0_76:
	s_mul_hi_i32 s2, s6, 0x2e8ba2e9
	s_lshr_b32 s3, s2, 31
	s_ashr_i32 s2, s2, 3
	s_add_i32 s3, s2, s3
	s_mul_i32 s2, s3, 0xfffff500
	s_add_i32 s2, s7, s2
	s_lshl_b32 s4, s3, 6
	v_add_u32_e32 v24, s2, v4
	s_ashr_i32 s5, s4, 31
	v_ashrrev_i32_e32 v25, 31, v24
	v_lshl_add_u64 v[22:23], s[4:5], 2, v[0:1]
	v_lshlrev_b64 v[18:19], 12, v[24:25]
	v_lshl_add_u64 v[18:19], v[22:23], 0, v[18:19]
	global_load_dwordx4 v[18:21], v[18:19], off nt
	s_ashr_i32 s3, s2, 31
	s_add_i32 s6, s6, s10
	s_add_i32 s7, s7, s11
	s_cmpk_lt_i32 s6, 0x2c0
	v_add_u32_e32 v100, 16, v24
	v_ashrrev_i32_e32 v101, 31, v100
	v_lshlrev_b64 v[100:101], 12, v[100:101]
	v_lshl_add_u64 v[100:101], v[22:23], 0, v[100:101]
	global_load_dwordx4 v[100:103], v[100:101], off nt
	v_add_u32_e32 v104, 32, v24
	v_ashrrev_i32_e32 v105, 31, v104
	v_lshlrev_b64 v[104:105], 12, v[104:105]
	v_lshl_add_u64 v[104:105], v[22:23], 0, v[104:105]
	global_load_dwordx4 v[104:107], v[104:105], off nt
	v_add_u32_e32 v108, 48, v24
	v_ashrrev_i32_e32 v109, 31, v108
	v_lshlrev_b64 v[108:109], 12, v[108:109]
	v_lshl_add_u64 v[108:109], v[22:23], 0, v[108:109]
	global_load_dwordx4 v[108:111], v[108:109], off nt
	s_barrier
	s_waitcnt vmcnt(3)
	ds_write2_b32 v6, v18, v19 offset1:1
	ds_write2_b32 v6, v20, v21 offset0:2 offset1:3
	s_waitcnt vmcnt(2)
	ds_write2_b32 v7, v100, v101 offset1:1
	ds_write2_b32 v7, v102, v103 offset0:2 offset1:3
	s_waitcnt vmcnt(1)
	ds_write2_b32 v8, v104, v105 offset1:1
	ds_write2_b32 v8, v106, v107 offset0:2 offset1:3
	s_waitcnt vmcnt(0)
	ds_write2_b32 v9, v108, v109 offset1:1
	ds_write2_b32 v9, v110, v111 offset0:2 offset1:3
	s_waitcnt lgkmcnt(0)
	s_barrier
	ds_read2_b32 v[18:19], v10 offset1:130
	ds_read2_b32 v[20:21], v11 offset0:65 offset1:195
	s_waitcnt lgkmcnt(0)
	v_cvt_pk_bf16_f32 v18, v18, v20
	v_cvt_pk_bf16_f32 v19, v19, v21
	ds_read2_b32 v[20:21], v12 offset0:4 offset1:134
	ds_read2_b32 v[22:23], v13 offset0:69 offset1:199
	s_waitcnt lgkmcnt(0)
	v_cvt_pk_bf16_f32 v20, v20, v22
	v_cvt_pk_bf16_f32 v21, v21, v23
	ds_read2_b32 v[22:23], v14 offset0:8 offset1:138
	ds_read2_b32 v[24:25], v15 offset0:73 offset1:203
	s_waitcnt lgkmcnt(0)
	v_cvt_pk_bf16_f32 v22, v22, v24
	v_cvt_pk_bf16_f32 v23, v23, v25
	ds_read2_b32 v[24:25], v16 offset0:12 offset1:142
	ds_read2_b32 v[26:27], v17 offset0:77 offset1:207
	s_waitcnt lgkmcnt(0)
	v_cvt_pk_bf16_f32 v24, v24, v26
	v_add_u32_e32 v26, s4, v5
	v_cvt_pk_bf16_f32 v25, v25, v27
	v_mad_i64_i32 v[26:27], s[4:5], v26, s12, v[2:3]
	v_lshl_add_u64 v[26:27], s[2:3], 1, v[26:27]
	v_lshl_add_u64 v[26:27], v[26:27], 0, v[128:129]
	global_store_dwordx4 v[26:27], v[18:21], off
	global_store_dwordx4 v[26:27], v[22:25], off offset:16
	s_cbranch_scc1 .LBB0_76

.LBB0_1822:
	s_ashr_i32 s2, s4, 31
	s_lshr_b32 s2, s2, 28
	s_add_i32 s2, s4, s2
	s_ashr_i32 s2, s2, 4
	s_lshl_b32 s6, s2, 10
	s_lshl_b32 s2, s2, 6
	s_ashr_i32 s3, s2, 31
	v_lshl_add_u64 v[6:7], s[2:3], 2, v[0:1]
	s_sub_i32 s3, s5, s6
	v_add_u32_e32 v8, s3, v20
	s_movk_i32 s3, 0x5800
	v_mad_i64_i32 v[2:3], s[12:13], v8, s3, v[6:7]
	global_load_dwordx4 v[2:5], v[2:3], off nt
	v_add_u32_e32 v12, 0x800, v28
	v_add_u32_e32 v14, 0xc00, v27
	v_add_u32_e32 v16, 0xc00, v28
	v_add_u32_e32 v18, s2, v21
	s_movk_i32 s2, 0xaff
	v_cmp_lt_i32_e32 vcc, s2, v18
	v_lshlrev_b32_e32 v19, 1, v18
	v_add_u32_e32 v100, 16, v8
	v_mad_i64_i32 v[100:101], s[12:13], v100, s3, v[6:7]
	global_load_dwordx4 v[100:103], v[100:101], off nt
	v_add_u32_e32 v104, 32, v8
	v_mad_i64_i32 v[104:105], s[12:13], v104, s3, v[6:7]
	global_load_dwordx4 v[104:107], v[104:105], off nt
	v_add_u32_e32 v108, 48, v8
	v_mad_i64_i32 v[108:109], s[12:13], v108, s3, v[6:7]
	global_load_dwordx4 v[108:111], v[108:109], off nt
	v_add_u32_e32 v8, 0x400, v28
	v_add_u32_e32 v6, 0x400, v27
	s_barrier
	s_waitcnt vmcnt(3)
	ds_write2_b32 v23, v2, v3 offset1:1
	ds_write2_b32 v23, v4, v5 offset0:2 offset1:3
	s_waitcnt vmcnt(2)
	ds_write2_b32 v24, v100, v101 offset1:1
	ds_write2_b32 v24, v102, v103 offset0:2 offset1:3
	s_waitcnt vmcnt(1)
	ds_write2_b32 v25, v104, v105 offset1:1
	ds_write2_b32 v25, v106, v107 offset0:2 offset1:3
	s_waitcnt vmcnt(0)
	ds_write2_b32 v26, v108, v109 offset1:1
	ds_write2_b32 v26, v110, v111 offset0:2 offset1:3
	s_waitcnt lgkmcnt(0)
	s_barrier
	ds_read2_b32 v[2:3], v27 offset1:130
	ds_read2_b32 v[4:5], v28 offset0:65 offset1:195
	ds_read2_b32 v[10:11], v8 offset0:69 offset1:199
	v_add_u32_e32 v8, 0x800, v27
	ds_read2_b32 v[6:7], v6 offset0:4 offset1:134
	ds_read2_b32 v[8:9], v8 offset0:8 offset1:138
	ds_read2_b32 v[12:13], v12 offset0:73 offset1:203
	ds_read2_b32 v[14:15], v14 offset0:12 offset1:142
	ds_read2_b32 v[16:17], v16 offset0:77 offset1:207
	s_and_saveexec_b64 s[2:3], vcc
	s_xor_b64 s[2:3], exec, s[2:3]
	v_add_u32_e32 v18, 0x7fffea00, v19
	s_mov_b32 s7, 0x7fffffc0
	v_and_or_b32 v18, v18, s7, v29
	s_andn2_saveexec_b64 s[2:3], s[2:3]
	s_cbranch_execz .LBB0_1821
	s_movk_i32 s7, 0xffc0
	v_and_or_b32 v18, v19, s7, v22
	s_branch .LBB0_1821

.LBB0_1828:
	s_mul_hi_i32 s2, s6, 0x2e8ba2e9
	s_lshr_b32 s3, s2, 31
	s_ashr_i32 s2, s2, 3
	s_add_i32 s3, s2, s3
	s_mul_i32 s2, s3, 0xfffff500
	s_add_i32 s2, s7, s2
	s_lshl_b32 s4, s3, 6
	v_add_u32_e32 v16, s2, v2
	s_ashr_i32 s5, s4, 31
	v_ashrrev_i32_e32 v17, 31, v16
	v_lshl_add_u64 v[14:15], s[4:5], 2, v[0:1]
	v_lshlrev_b64 v[10:11], 12, v[16:17]
	v_lshl_add_u64 v[10:11], v[14:15], 0, v[10:11]
	global_load_dwordx4 v[10:13], v[10:11], off nt
	v_add_u32_e32 v18, 0xc00, v9
	v_add_u32_e32 v20, s4, v3
	s_ashr_i32 s3, s2, 31
	s_add_i32 s6, s6, s13
	s_add_i32 s7, s7, s14
	s_cmpk_lt_i32 s6, 0x2c0
	v_add_u32_e32 v100, 16, v16
	v_ashrrev_i32_e32 v101, 31, v100
	v_lshlrev_b64 v[100:101], 12, v[100:101]
	v_lshl_add_u64 v[100:101], v[14:15], 0, v[100:101]
	global_load_dwordx4 v[100:103], v[100:101], off nt
	v_add_u32_e32 v104, 32, v16
	v_ashrrev_i32_e32 v105, 31, v104
	v_lshlrev_b64 v[104:105], 12, v[104:105]
	v_lshl_add_u64 v[104:105], v[14:15], 0, v[104:105]
	global_load_dwordx4 v[104:107], v[104:105], off nt
	v_add_u32_e32 v108, 48, v16
	v_ashrrev_i32_e32 v109, 31, v108
	v_lshlrev_b64 v[108:109], 12, v[108:109]
	v_lshl_add_u64 v[108:109], v[14:15], 0, v[108:109]
	global_load_dwordx4 v[108:111], v[108:109], off nt
	v_add_u32_e32 v14, 0x400, v9
	v_add_u32_e32 v16, 0x800, v9
	s_barrier
	s_waitcnt vmcnt(3)
	ds_write2_b32 v4, v10, v11 offset1:1
	ds_write2_b32 v4, v12, v13 offset0:2 offset1:3
	s_waitcnt vmcnt(2)
	ds_write2_b32 v5, v100, v101 offset1:1
	ds_write2_b32 v5, v102, v103 offset0:2 offset1:3
	s_waitcnt vmcnt(1)
	ds_write2_b32 v6, v104, v105 offset1:1
	ds_write2_b32 v6, v106, v107 offset0:2 offset1:3
	s_waitcnt vmcnt(0)
	ds_write2_b32 v7, v108, v109 offset1:1
	ds_write2_b32 v7, v110, v111 offset0:2 offset1:3
	s_waitcnt lgkmcnt(0)
	s_barrier
	ds_read2_b32 v[10:11], v8 offset1:130
	ds_read2_b32 v[12:13], v9 offset0:65 offset1:195
	ds_read2_b32 v[14:15], v14 offset0:69 offset1:199
	ds_read2_b32 v[16:17], v16 offset0:73 offset1:203
	ds_read2_b32 v[18:19], v18 offset0:77 offset1:207
	s_waitcnt lgkmcnt(3)
	v_cvt_pk_bf16_f32 v10, v10, v12
	v_add_u32_e32 v12, 0x400, v8
	v_cvt_pk_bf16_f32 v11, v11, v13
	ds_read2_b32 v[12:13], v12 offset0:4 offset1:134
	s_waitcnt lgkmcnt(0)
	v_cvt_pk_bf16_f32 v12, v12, v14
	v_add_u32_e32 v14, 0x800, v8
	v_cvt_pk_bf16_f32 v13, v13, v15
	ds_read2_b32 v[14:15], v14 offset0:8 offset1:138
	s_waitcnt lgkmcnt(0)
	v_cvt_pk_bf16_f32 v14, v14, v16
	v_add_u32_e32 v16, 0xc00, v8
	v_cvt_pk_bf16_f32 v15, v15, v17
	ds_read2_b32 v[16:17], v16 offset0:12 offset1:142
	s_waitcnt lgkmcnt(0)
	v_cvt_pk_bf16_f32 v16, v16, v18
	v_cvt_pk_bf16_f32 v17, v17, v19
	v_mov_b64_e32 v[18:19], s[0:1]
	v_mad_i64_i32 v[18:19], s[4:5], v20, s15, v[18:19]
	v_lshl_add_u64 v[18:19], s[2:3], 1, v[18:19]
	v_lshl_add_u64 v[18:19], v[18:19], 0, v[128:129]
	global_store_dwordx4 v[18:19], v[10:13], off
	global_store_dwordx4 v[18:19], v[14:17], off offset:16
	s_cbranch_scc1 .LBB0_1828

.LBB0_1837:
	s_ashr_i32 s2, s4, 31
	s_lshr_b32 s2, s2, 28
	s_add_i32 s2, s4, s2
	s_ashr_i32 s2, s2, 4
	s_lshl_b32 s12, s2, 10
	s_lshl_b32 s2, s2, 6
	s_ashr_i32 s3, s2, 31
	v_lshl_add_u64 v[6:7], s[2:3], 2, v[0:1]
	s_sub_i32 s3, s6, s12
	v_add_u32_e32 v8, s3, v20
	s_movk_i32 s3, 0x5800
	v_mad_i64_i32 v[2:3], s[14:15], v8, s3, v[6:7]
	global_load_dwordx4 v[2:5], v[2:3], off nt
	v_add_u32_e32 v12, 0x800, v28
	v_add_u32_e32 v14, 0xc00, v27
	v_add_u32_e32 v16, 0xc00, v28
	v_add_u32_e32 v18, s2, v21
	s_movk_i32 s2, 0xaff
	v_cmp_lt_i32_e32 vcc, s2, v18
	v_lshlrev_b32_e32 v19, 1, v18
	v_add_u32_e32 v100, 16, v8
	v_mad_i64_i32 v[100:101], s[14:15], v100, s3, v[6:7]
	global_load_dwordx4 v[100:103], v[100:101], off nt
	v_add_u32_e32 v104, 32, v8
	v_mad_i64_i32 v[104:105], s[14:15], v104, s3, v[6:7]
	global_load_dwordx4 v[104:107], v[104:105], off nt
	v_add_u32_e32 v108, 48, v8
	v_mad_i64_i32 v[108:109], s[14:15], v108, s3, v[6:7]
	global_load_dwordx4 v[108:111], v[108:109], off nt
	v_add_u32_e32 v8, 0x400, v28
	v_add_u32_e32 v6, 0x400, v27
	s_barrier
	s_waitcnt vmcnt(3)
	ds_write2_b32 v23, v2, v3 offset1:1
	ds_write2_b32 v23, v4, v5 offset0:2 offset1:3
	s_waitcnt vmcnt(2)
	ds_write2_b32 v24, v100, v101 offset1:1
	ds_write2_b32 v24, v102, v103 offset0:2 offset1:3
	s_waitcnt vmcnt(1)
	ds_write2_b32 v25, v104, v105 offset1:1
	ds_write2_b32 v25, v106, v107 offset0:2 offset1:3
	s_waitcnt vmcnt(0)
	ds_write2_b32 v26, v108, v109 offset1:1
	ds_write2_b32 v26, v110, v111 offset0:2 offset1:3
	s_waitcnt lgkmcnt(0)
	s_barrier
	ds_read2_b32 v[2:3], v27 offset1:130
	ds_read2_b32 v[4:5], v28 offset0:65 offset1:195
	ds_read2_b32 v[10:11], v8 offset0:69 offset1:199
	v_add_u32_e32 v8, 0x800, v27
	ds_read2_b32 v[6:7], v6 offset0:4 offset1:134
	ds_read2_b32 v[8:9], v8 offset0:8 offset1:138
	ds_read2_b32 v[12:13], v12 offset0:73 offset1:203
	ds_read2_b32 v[14:15], v14 offset0:12 offset1:142
	ds_read2_b32 v[16:17], v16 offset0:77 offset1:207
	s_and_saveexec_b64 s[2:3], vcc
	s_xor_b64 s[2:3], exec, s[2:3]
	v_add_u32_e32 v18, 0x7fffea00, v19
	s_mov_b32 s13, 0x7fffffc0
	v_and_or_b32 v18, v18, s13, v29
	s_andn2_saveexec_b64 s[2:3], s[2:3]
	s_cbranch_execz .LBB0_1836
	s_movk_i32 s13, 0xffc0
	v_and_or_b32 v18, v19, s13, v22
	s_branch .LBB0_1836

.LBB0_1845:
	s_mul_hi_i32 s2, s6, 0x2e8ba2e9
	s_lshr_b32 s3, s2, 31
	s_ashr_i32 s2, s2, 3
	s_add_i32 s3, s2, s3
	s_mul_i32 s2, s3, 0xfffff500
	s_add_i32 s2, s12, s2
	s_lshl_b32 s4, s3, 6
	v_add_u32_e32 v16, s2, v2
	s_ashr_i32 s5, s4, 31
	v_ashrrev_i32_e32 v17, 31, v16
	v_lshl_add_u64 v[14:15], s[4:5], 2, v[0:1]
	v_lshlrev_b64 v[10:11], 12, v[16:17]
	v_lshl_add_u64 v[10:11], v[14:15], 0, v[10:11]
	global_load_dwordx4 v[10:13], v[10:11], off nt
	v_add_u32_e32 v18, 0xc00, v9
	v_add_u32_e32 v20, s4, v3
	s_ashr_i32 s3, s2, 31
	s_add_i32 s6, s6, s7
	s_add_i32 s12, s12, s13
	s_cmpk_gt_i32 s6, 0x2bf
	v_add_u32_e32 v100, 16, v16
	v_ashrrev_i32_e32 v101, 31, v100
	v_lshlrev_b64 v[100:101], 12, v[100:101]
	v_lshl_add_u64 v[100:101], v[14:15], 0, v[100:101]
	global_load_dwordx4 v[100:103], v[100:101], off nt
	v_add_u32_e32 v104, 32, v16
	v_ashrrev_i32_e32 v105, 31, v104
	v_lshlrev_b64 v[104:105], 12, v[104:105]
	v_lshl_add_u64 v[104:105], v[14:15], 0, v[104:105]
	global_load_dwordx4 v[104:107], v[104:105], off nt
	v_add_u32_e32 v108, 48, v16
	v_ashrrev_i32_e32 v109, 31, v108
	v_lshlrev_b64 v[108:109], 12, v[108:109]
	v_lshl_add_u64 v[108:109], v[14:15], 0, v[108:109]
	global_load_dwordx4 v[108:111], v[108:109], off nt
	v_add_u32_e32 v14, 0x400, v9
	v_add_u32_e32 v16, 0x800, v9
	s_barrier
	s_waitcnt vmcnt(3)
	ds_write2_b32 v4, v10, v11 offset1:1
	ds_write2_b32 v4, v12, v13 offset0:2 offset1:3
	s_waitcnt vmcnt(2)
	ds_write2_b32 v5, v100, v101 offset1:1
	ds_write2_b32 v5, v102, v103 offset0:2 offset1:3
	s_waitcnt vmcnt(1)
	ds_write2_b32 v6, v104, v105 offset1:1
	ds_write2_b32 v6, v106, v107 offset0:2 offset1:3
	s_waitcnt vmcnt(0)
	ds_write2_b32 v7, v108, v109 offset1:1
	ds_write2_b32 v7, v110, v111 offset0:2 offset1:3
	s_waitcnt lgkmcnt(0)
	s_barrier
	ds_read2_b32 v[10:11], v8 offset1:130
	ds_read2_b32 v[12:13], v9 offset0:65 offset1:195
	ds_read2_b32 v[14:15], v14 offset0:69 offset1:199
	ds_read2_b32 v[16:17], v16 offset0:73 offset1:203
	ds_read2_b32 v[18:19], v18 offset0:77 offset1:207
	s_waitcnt lgkmcnt(3)
	v_cvt_pk_bf16_f32 v10, v10, v12
	v_add_u32_e32 v12, 0x400, v8
	v_cvt_pk_bf16_f32 v11, v11, v13
	ds_read2_b32 v[12:13], v12 offset0:4 offset1:134
	s_waitcnt lgkmcnt(0)
	v_cvt_pk_bf16_f32 v12, v12, v14
	v_add_u32_e32 v14, 0x800, v8
	v_cvt_pk_bf16_f32 v13, v13, v15
	ds_read2_b32 v[14:15], v14 offset0:8 offset1:138
	s_waitcnt lgkmcnt(0)
	v_cvt_pk_bf16_f32 v14, v14, v16
	v_add_u32_e32 v16, 0xc00, v8
	v_cvt_pk_bf16_f32 v15, v15, v17
	ds_read2_b32 v[16:17], v16 offset0:12 offset1:142
	s_waitcnt lgkmcnt(0)
	v_cvt_pk_bf16_f32 v16, v16, v18
	v_cvt_pk_bf16_f32 v17, v17, v19
	v_mov_b64_e32 v[18:19], s[0:1]
	v_mad_i64_i32 v[18:19], s[4:5], v20, s14, v[18:19]
	v_lshl_add_u64 v[18:19], s[2:3], 1, v[18:19]
	v_lshl_add_u64 v[18:19], v[18:19], 0, v[128:129]
	global_store_dwordx4 v[18:19], v[10:13], off
	global_store_dwordx4 v[18:19], v[14:17], off offset:16
	s_cbranch_scc0 .LBB0_1845

.LBB0_2354:
	s_ashr_i32 s6, s11, 31
	s_lshr_b32 s6, s6, 28
	s_add_i32 s6, s11, s6
	s_ashr_i32 s7, s6, 4
	s_lshl_b32 s6, s7, 10
	s_lshl_b32 s8, s7, 6
	s_sub_i32 s6, s12, s6
	s_ashr_i32 s9, s8, 31
	v_lshl_add_u64 v[14:15], s[8:9], 2, v[0:1]
	v_add_u32_e32 v16, s6, v2
	v_mad_i64_i32 v[10:11], s[14:15], v16, s17, v[14:15]
	global_load_dwordx4 v[10:13], v[10:11], off nt
	v_add_u32_e32 v18, 0xc00, v9
	s_ashr_i32 s7, s6, 31
	s_add_i32 s11, s11, s13
	s_add_i32 s12, s12, s16
	s_cmpk_lt_i32 s11, 0x300
	v_add_u32_e32 v100, 16, v16
	v_mad_i64_i32 v[100:101], s[14:15], v100, s17, v[14:15]
	global_load_dwordx4 v[100:103], v[100:101], off nt
	v_add_u32_e32 v104, 32, v16
	v_mad_i64_i32 v[104:105], s[14:15], v104, s17, v[14:15]
	global_load_dwordx4 v[104:107], v[104:105], off nt
	v_add_u32_e32 v108, 48, v16
	v_mad_i64_i32 v[108:109], s[14:15], v108, s17, v[14:15]
	global_load_dwordx4 v[108:111], v[108:109], off nt
	v_add_u32_e32 v14, 0x400, v9
	v_add_u32_e32 v16, 0x800, v9
	s_barrier
	s_waitcnt vmcnt(3)
	ds_write2_b32 v4, v10, v11 offset1:1
	ds_write2_b32 v4, v12, v13 offset0:2 offset1:3
	s_waitcnt vmcnt(2)
	ds_write2_b32 v5, v100, v101 offset1:1
	ds_write2_b32 v5, v102, v103 offset0:2 offset1:3
	s_waitcnt vmcnt(1)
	ds_write2_b32 v6, v104, v105 offset1:1
	ds_write2_b32 v6, v106, v107 offset0:2 offset1:3
	s_waitcnt vmcnt(0)
	ds_write2_b32 v7, v108, v109 offset1:1
	ds_write2_b32 v7, v110, v111 offset0:2 offset1:3
	s_waitcnt lgkmcnt(0)
	s_barrier
	ds_read2_b32 v[10:11], v8 offset1:130
	ds_read2_b32 v[12:13], v9 offset0:65 offset1:195
	ds_read2_b32 v[14:15], v14 offset0:69 offset1:199
	ds_read2_b32 v[16:17], v16 offset0:73 offset1:203
	ds_read2_b32 v[18:19], v18 offset0:77 offset1:207
	s_waitcnt lgkmcnt(3)
	v_cvt_pk_bf16_f32 v10, v10, v12
	v_add_u32_e32 v12, 0x400, v8
	v_cvt_pk_bf16_f32 v11, v11, v13
	ds_read2_b32 v[12:13], v12 offset0:4 offset1:134
	s_waitcnt lgkmcnt(0)
	v_cvt_pk_bf16_f32 v12, v12, v14
	v_add_u32_e32 v14, 0x800, v8
	v_cvt_pk_bf16_f32 v13, v13, v15
	ds_read2_b32 v[14:15], v14 offset0:8 offset1:138
	s_waitcnt lgkmcnt(0)
	v_cvt_pk_bf16_f32 v14, v14, v16
	v_add_u32_e32 v16, 0xc00, v8
	v_cvt_pk_bf16_f32 v15, v15, v17
	ds_read2_b32 v[16:17], v16 offset0:12 offset1:142
	s_waitcnt lgkmcnt(0)
	v_cvt_pk_bf16_f32 v16, v16, v18
	v_add_u32_e32 v18, s8, v3
	v_cvt_pk_bf16_f32 v17, v17, v19
	v_ashrrev_i32_e32 v19, 31, v18
	v_lshlrev_b64 v[18:19], 11, v[18:19]
	v_lshl_add_u64 v[18:19], s[2:3], 0, v[18:19]
	v_lshl_add_u64 v[18:19], s[6:7], 1, v[18:19]
	v_lshl_add_u64 v[18:19], v[18:19], 0, v[128:129]
	global_store_dwordx4 v[18:19], v[10:13], off
	global_store_dwordx4 v[18:19], v[14:17], off offset:16
	s_cbranch_scc1 .LBB0_2354

.LBB0_2357:
	s_ashr_i32 s6, s11, 31
	s_lshr_b32 s6, s6, 28
	s_add_i32 s6, s11, s6
	s_ashr_i32 s7, s6, 4
	s_lshl_b32 s6, s7, 10
	s_sub_i32 s6, s12, s6
	s_lshl_b32 s8, s7, 6
	v_add_u32_e32 v16, s6, v2
	s_ashr_i32 s9, s8, 31
	v_ashrrev_i32_e32 v17, 31, v16
	v_lshl_add_u64 v[14:15], s[8:9], 2, v[0:1]
	v_lshlrev_b64 v[10:11], 12, v[16:17]
	v_lshl_add_u64 v[10:11], v[14:15], 0, v[10:11]
	global_load_dwordx4 v[10:13], v[10:11], off nt
	v_add_u32_e32 v18, 0xc00, v9
	s_ashr_i32 s7, s6, 31
	s_add_i32 s11, s11, s13
	s_add_i32 s12, s12, s16
	s_cmpk_gt_i32 s11, 0xff
	v_add_u32_e32 v100, 16, v16
	v_ashrrev_i32_e32 v101, 31, v100
	v_lshlrev_b64 v[100:101], 12, v[100:101]
	v_lshl_add_u64 v[100:101], v[14:15], 0, v[100:101]
	global_load_dwordx4 v[100:103], v[100:101], off nt
	v_add_u32_e32 v104, 32, v16
	v_ashrrev_i32_e32 v105, 31, v104
	v_lshlrev_b64 v[104:105], 12, v[104:105]
	v_lshl_add_u64 v[104:105], v[14:15], 0, v[104:105]
	global_load_dwordx4 v[104:107], v[104:105], off nt
	v_add_u32_e32 v108, 48, v16
	v_ashrrev_i32_e32 v109, 31, v108
	v_lshlrev_b64 v[108:109], 12, v[108:109]
	v_lshl_add_u64 v[108:109], v[14:15], 0, v[108:109]
	global_load_dwordx4 v[108:111], v[108:109], off nt
	v_add_u32_e32 v14, 0x400, v9
	v_add_u32_e32 v16, 0x800, v9
	s_barrier
	s_waitcnt vmcnt(3)
	ds_write2_b32 v4, v10, v11 offset1:1
	ds_write2_b32 v4, v12, v13 offset0:2 offset1:3
	s_waitcnt vmcnt(2)
	ds_write2_b32 v5, v100, v101 offset1:1
	ds_write2_b32 v5, v102, v103 offset0:2 offset1:3
	s_waitcnt vmcnt(1)
	ds_write2_b32 v6, v104, v105 offset1:1
	ds_write2_b32 v6, v106, v107 offset0:2 offset1:3
	s_waitcnt vmcnt(0)
	ds_write2_b32 v7, v108, v109 offset1:1
	ds_write2_b32 v7, v110, v111 offset0:2 offset1:3
	s_waitcnt lgkmcnt(0)
	s_barrier
	ds_read2_b32 v[10:11], v8 offset1:130
	ds_read2_b32 v[12:13], v9 offset0:65 offset1:195
	ds_read2_b32 v[14:15], v14 offset0:69 offset1:199
	ds_read2_b32 v[16:17], v16 offset0:73 offset1:203
	ds_read2_b32 v[18:19], v18 offset0:77 offset1:207
	s_waitcnt lgkmcnt(3)
	v_cvt_pk_bf16_f32 v10, v10, v12
	v_add_u32_e32 v12, 0x400, v8
	v_cvt_pk_bf16_f32 v11, v11, v13
	ds_read2_b32 v[12:13], v12 offset0:4 offset1:134
	s_waitcnt lgkmcnt(0)
	v_cvt_pk_bf16_f32 v12, v12, v14
	v_add_u32_e32 v14, 0x800, v8
	v_cvt_pk_bf16_f32 v13, v13, v15
	ds_read2_b32 v[14:15], v14 offset0:8 offset1:138
	s_waitcnt lgkmcnt(0)
	v_cvt_pk_bf16_f32 v14, v14, v16
	v_add_u32_e32 v16, 0xc00, v8
	v_cvt_pk_bf16_f32 v15, v15, v17
	ds_read2_b32 v[16:17], v16 offset0:12 offset1:142
	s_waitcnt lgkmcnt(0)
	v_cvt_pk_bf16_f32 v16, v16, v18
	v_add_u32_e32 v18, s8, v3
	v_cvt_pk_bf16_f32 v17, v17, v19
	v_ashrrev_i32_e32 v19, 31, v18
	v_lshlrev_b64 v[18:19], 11, v[18:19]
	v_lshl_add_u64 v[18:19], s[2:3], 0, v[18:19]
	v_lshl_add_u64 v[18:19], s[6:7], 1, v[18:19]
	v_lshl_add_u64 v[18:19], v[18:19], 0, v[128:129]
	global_store_dwordx4 v[18:19], v[10:13], off
	global_store_dwordx4 v[18:19], v[14:17], off offset:16
	s_cbranch_scc0 .LBB0_2357

.LBB0_2363:
	s_ashr_i32 s2, s8, 31
	s_lshr_b32 s2, s2, 28
	s_add_i32 s2, s8, s2
	s_ashr_i32 s3, s2, 4
	s_lshl_b32 s2, s3, 10
	s_lshl_b32 s6, s3, 6
	s_sub_i32 s2, s9, s2
	s_ashr_i32 s7, s6, 31
	v_lshl_add_u64 v[14:15], s[6:7], 2, v[0:1]
	v_add_u32_e32 v16, s2, v2
	v_mad_i64_i32 v[10:11], s[10:11], v16, s14, v[14:15]
	global_load_dwordx4 v[10:13], v[10:11], off nt
	v_add_u32_e32 v18, 0xc00, v9
	s_ashr_i32 s3, s2, 31
	s_add_i32 s8, s8, s12
	s_add_i32 s9, s9, s13
	s_cmpk_lt_i32 s8, 0x300
	v_add_u32_e32 v100, 16, v16
	v_mad_i64_i32 v[100:101], s[10:11], v100, s14, v[14:15]
	global_load_dwordx4 v[100:103], v[100:101], off nt
	v_add_u32_e32 v104, 32, v16
	v_mad_i64_i32 v[104:105], s[10:11], v104, s14, v[14:15]
	global_load_dwordx4 v[104:107], v[104:105], off nt
	v_add_u32_e32 v108, 48, v16
	v_mad_i64_i32 v[108:109], s[10:11], v108, s14, v[14:15]
	global_load_dwordx4 v[108:111], v[108:109], off nt
	v_add_u32_e32 v14, 0x400, v9
	v_add_u32_e32 v16, 0x800, v9
	s_barrier
	s_waitcnt vmcnt(3)
	ds_write2_b32 v4, v10, v11 offset1:1
	ds_write2_b32 v4, v12, v13 offset0:2 offset1:3
	s_waitcnt vmcnt(2)
	ds_write2_b32 v5, v100, v101 offset1:1
	ds_write2_b32 v5, v102, v103 offset0:2 offset1:3
	s_waitcnt vmcnt(1)
	ds_write2_b32 v6, v104, v105 offset1:1
	ds_write2_b32 v6, v106, v107 offset0:2 offset1:3
	s_waitcnt vmcnt(0)
	ds_write2_b32 v7, v108, v109 offset1:1
	ds_write2_b32 v7, v110, v111 offset0:2 offset1:3
	s_waitcnt lgkmcnt(0)
	s_barrier
	ds_read2_b32 v[10:11], v8 offset1:130
	ds_read2_b32 v[12:13], v9 offset0:65 offset1:195
	ds_read2_b32 v[14:15], v14 offset0:69 offset1:199
	ds_read2_b32 v[16:17], v16 offset0:73 offset1:203
	ds_read2_b32 v[18:19], v18 offset0:77 offset1:207
	s_waitcnt lgkmcnt(3)
	v_cvt_pk_bf16_f32 v10, v10, v12
	v_add_u32_e32 v12, 0x400, v8
	v_cvt_pk_bf16_f32 v11, v11, v13
	ds_read2_b32 v[12:13], v12 offset0:4 offset1:134
	s_waitcnt lgkmcnt(0)
	v_cvt_pk_bf16_f32 v12, v12, v14
	v_add_u32_e32 v14, 0x800, v8
	v_cvt_pk_bf16_f32 v13, v13, v15
	ds_read2_b32 v[14:15], v14 offset0:8 offset1:138
	s_waitcnt lgkmcnt(0)
	v_cvt_pk_bf16_f32 v14, v14, v16
	v_add_u32_e32 v16, 0xc00, v8
	v_cvt_pk_bf16_f32 v15, v15, v17
	ds_read2_b32 v[16:17], v16 offset0:12 offset1:142
	s_waitcnt lgkmcnt(0)
	v_cvt_pk_bf16_f32 v16, v16, v18
	v_add_u32_e32 v18, s6, v3
	v_cvt_pk_bf16_f32 v17, v17, v19
	v_ashrrev_i32_e32 v19, 31, v18
	v_lshlrev_b64 v[18:19], 11, v[18:19]
	v_lshl_add_u64 v[18:19], s[0:1], 0, v[18:19]
	v_lshl_add_u64 v[18:19], s[2:3], 1, v[18:19]
	v_lshl_add_u64 v[18:19], v[18:19], 0, v[128:129]
	global_store_dwordx4 v[18:19], v[10:13], off
	global_store_dwordx4 v[18:19], v[14:17], off offset:16
	s_cbranch_scc1 .LBB0_2363

.LBB0_2366:
	s_ashr_i32 s2, s8, 31
	s_lshr_b32 s2, s2, 28
	s_add_i32 s2, s8, s2
	s_ashr_i32 s3, s2, 4
	s_lshl_b32 s2, s3, 10
	s_sub_i32 s2, s9, s2
	s_lshl_b32 s6, s3, 6
	v_add_u32_e32 v16, s2, v2
	s_ashr_i32 s7, s6, 31
	v_ashrrev_i32_e32 v17, 31, v16
	v_lshl_add_u64 v[14:15], s[6:7], 2, v[0:1]
	v_lshlrev_b64 v[10:11], 12, v[16:17]
	v_lshl_add_u64 v[10:11], v[14:15], 0, v[10:11]
	global_load_dwordx4 v[10:13], v[10:11], off nt
	v_add_u32_e32 v18, 0xc00, v9
	s_ashr_i32 s3, s2, 31
	s_add_i32 s8, s8, s12
	s_add_i32 s9, s9, s13
	s_cmpk_gt_i32 s8, 0xff
	v_add_u32_e32 v100, 16, v16
	v_ashrrev_i32_e32 v101, 31, v100
	v_lshlrev_b64 v[100:101], 12, v[100:101]
	v_lshl_add_u64 v[100:101], v[14:15], 0, v[100:101]
	global_load_dwordx4 v[100:103], v[100:101], off nt
	v_add_u32_e32 v104, 32, v16
	v_ashrrev_i32_e32 v105, 31, v104
	v_lshlrev_b64 v[104:105], 12, v[104:105]
	v_lshl_add_u64 v[104:105], v[14:15], 0, v[104:105]
	global_load_dwordx4 v[104:107], v[104:105], off nt
	v_add_u32_e32 v108, 48, v16
	v_ashrrev_i32_e32 v109, 31, v108
	v_lshlrev_b64 v[108:109], 12, v[108:109]
	v_lshl_add_u64 v[108:109], v[14:15], 0, v[108:109]
	global_load_dwordx4 v[108:111], v[108:109], off nt
	v_add_u32_e32 v14, 0x400, v9
	v_add_u32_e32 v16, 0x800, v9
	s_barrier
	s_waitcnt vmcnt(3)
	ds_write2_b32 v4, v10, v11 offset1:1
	ds_write2_b32 v4, v12, v13 offset0:2 offset1:3
	s_waitcnt vmcnt(2)
	ds_write2_b32 v5, v100, v101 offset1:1
	ds_write2_b32 v5, v102, v103 offset0:2 offset1:3
	s_waitcnt vmcnt(1)
	ds_write2_b32 v6, v104, v105 offset1:1
	ds_write2_b32 v6, v106, v107 offset0:2 offset1:3
	s_waitcnt vmcnt(0)
	ds_write2_b32 v7, v108, v109 offset1:1
	ds_write2_b32 v7, v110, v111 offset0:2 offset1:3
	s_waitcnt lgkmcnt(0)
	s_barrier
	ds_read2_b32 v[10:11], v8 offset1:130
	ds_read2_b32 v[12:13], v9 offset0:65 offset1:195
	ds_read2_b32 v[14:15], v14 offset0:69 offset1:199
	ds_read2_b32 v[16:17], v16 offset0:73 offset1:203
	ds_read2_b32 v[18:19], v18 offset0:77 offset1:207
	s_waitcnt lgkmcnt(3)
	v_cvt_pk_bf16_f32 v10, v10, v12
	v_add_u32_e32 v12, 0x400, v8
	v_cvt_pk_bf16_f32 v11, v11, v13
	ds_read2_b32 v[12:13], v12 offset0:4 offset1:134
	s_waitcnt lgkmcnt(0)
	v_cvt_pk_bf16_f32 v12, v12, v14
	v_add_u32_e32 v14, 0x800, v8
	v_cvt_pk_bf16_f32 v13, v13, v15
	ds_read2_b32 v[14:15], v14 offset0:8 offset1:138
	s_waitcnt lgkmcnt(0)
	v_cvt_pk_bf16_f32 v14, v14, v16
	v_add_u32_e32 v16, 0xc00, v8
	v_cvt_pk_bf16_f32 v15, v15, v17
	ds_read2_b32 v[16:17], v16 offset0:12 offset1:142
	s_waitcnt lgkmcnt(0)
	v_cvt_pk_bf16_f32 v16, v16, v18
	v_add_u32_e32 v18, s6, v3
	v_cvt_pk_bf16_f32 v17, v17, v19
	v_ashrrev_i32_e32 v19, 31, v18
	v_lshlrev_b64 v[18:19], 11, v[18:19]
	v_lshl_add_u64 v[18:19], s[0:1], 0, v[18:19]
	v_lshl_add_u64 v[18:19], s[2:3], 1, v[18:19]
	v_lshl_add_u64 v[18:19], v[18:19], 0, v[128:129]
	global_store_dwordx4 v[18:19], v[10:13], off
	global_store_dwordx4 v[18:19], v[14:17], off offset:16
	s_cbranch_scc0 .LBB0_2366

.LBB0_2370:
	s_ashr_i32 s2, s8, 31
	s_lshr_b32 s2, s2, 28
	s_add_i32 s2, s8, s2
	s_ashr_i32 s3, s2, 4
	s_lshl_b32 s2, s3, 10
	s_lshl_b32 s6, s3, 6
	s_sub_i32 s2, s9, s2
	s_ashr_i32 s7, s6, 31
	v_lshl_add_u64 v[14:15], s[6:7], 2, v[0:1]
	v_add_u32_e32 v16, s2, v2
	v_mad_i64_i32 v[10:11], s[10:11], v16, s14, v[14:15]
	global_load_dwordx4 v[10:13], v[10:11], off nt
	v_add_u32_e32 v18, 0xc00, v9
	s_ashr_i32 s3, s2, 31
	s_add_i32 s8, s8, s12
	s_add_i32 s9, s9, s13
	s_cmpk_lt_i32 s8, 0x610
	v_add_u32_e32 v100, 16, v16
	v_mad_i64_i32 v[100:101], s[10:11], v100, s14, v[14:15]
	global_load_dwordx4 v[100:103], v[100:101], off nt
	v_add_u32_e32 v104, 32, v16
	v_mad_i64_i32 v[104:105], s[10:11], v104, s14, v[14:15]
	global_load_dwordx4 v[104:107], v[104:105], off nt
	v_add_u32_e32 v108, 48, v16
	v_mad_i64_i32 v[108:109], s[10:11], v108, s14, v[14:15]
	global_load_dwordx4 v[108:111], v[108:109], off nt
	v_add_u32_e32 v14, 0x400, v9
	v_add_u32_e32 v16, 0x800, v9
	s_barrier
	s_waitcnt vmcnt(3)
	ds_write2_b32 v4, v10, v11 offset1:1
	ds_write2_b32 v4, v12, v13 offset0:2 offset1:3
	s_waitcnt vmcnt(2)
	ds_write2_b32 v5, v100, v101 offset1:1
	ds_write2_b32 v5, v102, v103 offset0:2 offset1:3
	s_waitcnt vmcnt(1)
	ds_write2_b32 v6, v104, v105 offset1:1
	ds_write2_b32 v6, v106, v107 offset0:2 offset1:3
	s_waitcnt vmcnt(0)
	ds_write2_b32 v7, v108, v109 offset1:1
	ds_write2_b32 v7, v110, v111 offset0:2 offset1:3
	s_waitcnt lgkmcnt(0)
	s_barrier
	ds_read2_b32 v[10:11], v8 offset1:130
	ds_read2_b32 v[12:13], v9 offset0:65 offset1:195
	ds_read2_b32 v[14:15], v14 offset0:69 offset1:199
	ds_read2_b32 v[16:17], v16 offset0:73 offset1:203
	ds_read2_b32 v[18:19], v18 offset0:77 offset1:207
	s_waitcnt lgkmcnt(3)
	v_cvt_pk_bf16_f32 v10, v10, v12
	v_add_u32_e32 v12, 0x400, v8
	v_cvt_pk_bf16_f32 v11, v11, v13
	ds_read2_b32 v[12:13], v12 offset0:4 offset1:134
	s_waitcnt lgkmcnt(0)
	v_cvt_pk_bf16_f32 v12, v12, v14
	v_add_u32_e32 v14, 0x800, v8
	v_cvt_pk_bf16_f32 v13, v13, v15
	ds_read2_b32 v[14:15], v14 offset0:8 offset1:138
	s_waitcnt lgkmcnt(0)
	v_cvt_pk_bf16_f32 v14, v14, v16
	v_add_u32_e32 v16, 0xc00, v8
	v_cvt_pk_bf16_f32 v15, v15, v17
	ds_read2_b32 v[16:17], v16 offset0:12 offset1:142
	s_waitcnt lgkmcnt(0)
	v_cvt_pk_bf16_f32 v16, v16, v18
	v_add_u32_e32 v18, s6, v3
	v_cvt_pk_bf16_f32 v17, v17, v19
	v_ashrrev_i32_e32 v19, 31, v18
	v_lshlrev_b64 v[18:19], 11, v[18:19]
	v_lshl_add_u64 v[18:19], s[0:1], 0, v[18:19]
	v_lshl_add_u64 v[18:19], s[2:3], 1, v[18:19]
	v_lshl_add_u64 v[18:19], v[18:19], 0, v[128:129]
	global_store_dwordx4 v[18:19], v[10:13], off
	global_store_dwordx4 v[18:19], v[14:17], off offset:16
	s_cbranch_scc1 .LBB0_2370

.LBB0_2394:
	s_ashr_i32 s6, s11, 31
	s_lshr_b32 s6, s6, 28
	s_add_i32 s6, s11, s6
	s_ashr_i32 s7, s6, 4
	s_lshl_b32 s6, s7, 10
	s_lshl_b32 s8, s7, 6
	s_sub_i32 s6, s13, s6
	s_ashr_i32 s9, s8, 31
	v_lshl_add_u64 v[14:15], s[8:9], 2, v[0:1]
	v_add_u32_e32 v16, s6, v2
	v_mad_i64_i32 v[10:11], s[16:17], v16, s15, v[14:15]
	global_load_dwordx4 v[10:13], v[10:11], off nt
	v_add_u32_e32 v18, 0xc00, v9
	s_ashr_i32 s7, s6, 31
	s_add_i32 s11, s11, s12
	s_add_i32 s13, s13, s14
	s_cmpk_lt_i32 s11, 0x300
	v_add_u32_e32 v100, 16, v16
	v_mad_i64_i32 v[100:101], s[16:17], v100, s15, v[14:15]
	global_load_dwordx4 v[100:103], v[100:101], off nt
	v_add_u32_e32 v104, 32, v16
	v_mad_i64_i32 v[104:105], s[16:17], v104, s15, v[14:15]
	global_load_dwordx4 v[104:107], v[104:105], off nt
	v_add_u32_e32 v108, 48, v16
	v_mad_i64_i32 v[108:109], s[16:17], v108, s15, v[14:15]
	global_load_dwordx4 v[108:111], v[108:109], off nt
	v_add_u32_e32 v14, 0x400, v9
	v_add_u32_e32 v16, 0x800, v9
	s_barrier
	s_waitcnt vmcnt(3)
	ds_write2_b32 v4, v10, v11 offset1:1
	ds_write2_b32 v4, v12, v13 offset0:2 offset1:3
	s_waitcnt vmcnt(2)
	ds_write2_b32 v5, v100, v101 offset1:1
	ds_write2_b32 v5, v102, v103 offset0:2 offset1:3
	s_waitcnt vmcnt(1)
	ds_write2_b32 v6, v104, v105 offset1:1
	ds_write2_b32 v6, v106, v107 offset0:2 offset1:3
	s_waitcnt vmcnt(0)
	ds_write2_b32 v7, v108, v109 offset1:1
	ds_write2_b32 v7, v110, v111 offset0:2 offset1:3
	s_waitcnt lgkmcnt(0)
	s_barrier
	ds_read2_b32 v[10:11], v8 offset1:130
	ds_read2_b32 v[12:13], v9 offset0:65 offset1:195
	ds_read2_b32 v[14:15], v14 offset0:69 offset1:199
	ds_read2_b32 v[16:17], v16 offset0:73 offset1:203
	ds_read2_b32 v[18:19], v18 offset0:77 offset1:207
	s_waitcnt lgkmcnt(3)
	v_cvt_pk_bf16_f32 v10, v10, v12
	v_add_u32_e32 v12, 0x400, v8
	v_cvt_pk_bf16_f32 v11, v11, v13
	ds_read2_b32 v[12:13], v12 offset0:4 offset1:134
	s_waitcnt lgkmcnt(0)
	v_cvt_pk_bf16_f32 v12, v12, v14
	v_add_u32_e32 v14, 0x800, v8
	v_cvt_pk_bf16_f32 v13, v13, v15
	ds_read2_b32 v[14:15], v14 offset0:8 offset1:138
	s_waitcnt lgkmcnt(0)
	v_cvt_pk_bf16_f32 v14, v14, v16
	v_add_u32_e32 v16, 0xc00, v8
	v_cvt_pk_bf16_f32 v15, v15, v17
	ds_read2_b32 v[16:17], v16 offset0:12 offset1:142
	s_waitcnt lgkmcnt(0)
	v_cvt_pk_bf16_f32 v16, v16, v18
	v_add_u32_e32 v18, s8, v3
	v_cvt_pk_bf16_f32 v17, v17, v19
	v_ashrrev_i32_e32 v19, 31, v18
	v_lshlrev_b64 v[18:19], 11, v[18:19]
	v_lshl_add_u64 v[18:19], s[2:3], 0, v[18:19]
	v_lshl_add_u64 v[18:19], s[6:7], 1, v[18:19]
	v_lshl_add_u64 v[18:19], v[18:19], 0, v[128:129]
	global_store_dwordx4 v[18:19], v[10:13], off
	global_store_dwordx4 v[18:19], v[14:17], off offset:16
	s_cbranch_scc1 .LBB0_2394

.LBB0_2399:
	s_ashr_i32 s6, s11, 31
	s_lshr_b32 s6, s6, 28
	s_add_i32 s6, s11, s6
	s_ashr_i32 s7, s6, 4
	s_lshl_b32 s6, s7, 10
	s_sub_i32 s6, s13, s6
	s_lshl_b32 s8, s7, 6
	v_add_u32_e32 v16, s6, v2
	s_ashr_i32 s9, s8, 31
	v_ashrrev_i32_e32 v17, 31, v16
	v_lshl_add_u64 v[14:15], s[8:9], 2, v[0:1]
	v_lshlrev_b64 v[10:11], 12, v[16:17]
	v_lshl_add_u64 v[10:11], v[14:15], 0, v[10:11]
	global_load_dwordx4 v[10:13], v[10:11], off nt
	v_add_u32_e32 v18, 0xc00, v9
	s_ashr_i32 s7, s6, 31
	s_add_i32 s11, s11, s12
	s_add_i32 s13, s13, s14
	s_cmpk_gt_i32 s11, 0xff
	v_add_u32_e32 v100, 16, v16
	v_ashrrev_i32_e32 v101, 31, v100
	v_lshlrev_b64 v[100:101], 12, v[100:101]
	v_lshl_add_u64 v[100:101], v[14:15], 0, v[100:101]
	global_load_dwordx4 v[100:103], v[100:101], off nt
	v_add_u32_e32 v104, 32, v16
	v_ashrrev_i32_e32 v105, 31, v104
	v_lshlrev_b64 v[104:105], 12, v[104:105]
	v_lshl_add_u64 v[104:105], v[14:15], 0, v[104:105]
	global_load_dwordx4 v[104:107], v[104:105], off nt
	v_add_u32_e32 v108, 48, v16
	v_ashrrev_i32_e32 v109, 31, v108
	v_lshlrev_b64 v[108:109], 12, v[108:109]
	v_lshl_add_u64 v[108:109], v[14:15], 0, v[108:109]
	global_load_dwordx4 v[108:111], v[108:109], off nt
	v_add_u32_e32 v14, 0x400, v9
	v_add_u32_e32 v16, 0x800, v9
	s_barrier
	s_waitcnt vmcnt(3)
	ds_write2_b32 v4, v10, v11 offset1:1
	ds_write2_b32 v4, v12, v13 offset0:2 offset1:3
	s_waitcnt vmcnt(2)
	ds_write2_b32 v5, v100, v101 offset1:1
	ds_write2_b32 v5, v102, v103 offset0:2 offset1:3
	s_waitcnt vmcnt(1)
	ds_write2_b32 v6, v104, v105 offset1:1
	ds_write2_b32 v6, v106, v107 offset0:2 offset1:3
	s_waitcnt vmcnt(0)
	ds_write2_b32 v7, v108, v109 offset1:1
	ds_write2_b32 v7, v110, v111 offset0:2 offset1:3
	s_waitcnt lgkmcnt(0)
	s_barrier
	ds_read2_b32 v[10:11], v8 offset1:130
	ds_read2_b32 v[12:13], v9 offset0:65 offset1:195
	ds_read2_b32 v[14:15], v14 offset0:69 offset1:199
	ds_read2_b32 v[16:17], v16 offset0:73 offset1:203
	ds_read2_b32 v[18:19], v18 offset0:77 offset1:207
	s_waitcnt lgkmcnt(3)
	v_cvt_pk_bf16_f32 v10, v10, v12
	v_add_u32_e32 v12, 0x400, v8
	v_cvt_pk_bf16_f32 v11, v11, v13
	ds_read2_b32 v[12:13], v12 offset0:4 offset1:134
	s_waitcnt lgkmcnt(0)
	v_cvt_pk_bf16_f32 v12, v12, v14
	v_add_u32_e32 v14, 0x800, v8
	v_cvt_pk_bf16_f32 v13, v13, v15
	ds_read2_b32 v[14:15], v14 offset0:8 offset1:138
	s_waitcnt lgkmcnt(0)
	v_cvt_pk_bf16_f32 v14, v14, v16
	v_add_u32_e32 v16, 0xc00, v8
	v_cvt_pk_bf16_f32 v15, v15, v17
	ds_read2_b32 v[16:17], v16 offset0:12 offset1:142
	s_waitcnt lgkmcnt(0)
	v_cvt_pk_bf16_f32 v16, v16, v18
	v_add_u32_e32 v18, s8, v3
	v_cvt_pk_bf16_f32 v17, v17, v19
	v_ashrrev_i32_e32 v19, 31, v18
	v_lshlrev_b64 v[18:19], 11, v[18:19]
	v_lshl_add_u64 v[18:19], s[2:3], 0, v[18:19]
	v_lshl_add_u64 v[18:19], s[6:7], 1, v[18:19]
	v_lshl_add_u64 v[18:19], v[18:19], 0, v[128:129]
	global_store_dwordx4 v[18:19], v[10:13], off
	global_store_dwordx4 v[18:19], v[14:17], off offset:16
	s_cbranch_scc0 .LBB0_2399

.LBB0_2407:
	s_ashr_i32 s2, s8, 31
	s_lshr_b32 s2, s2, 28
	s_add_i32 s2, s8, s2
	s_ashr_i32 s3, s2, 4
	s_lshl_b32 s2, s3, 10
	s_lshl_b32 s6, s3, 6
	s_sub_i32 s2, s10, s2
	s_ashr_i32 s7, s6, 31
	v_lshl_add_u64 v[14:15], s[6:7], 2, v[0:1]
	v_add_u32_e32 v16, s2, v2
	v_mad_i64_i32 v[10:11], s[12:13], v16, s14, v[14:15]
	global_load_dwordx4 v[10:13], v[10:11], off nt
	v_add_u32_e32 v18, 0xc00, v9
	s_ashr_i32 s3, s2, 31
	s_add_i32 s8, s8, s9
	s_add_i32 s10, s10, s11
	s_cmpk_lt_i32 s8, 0x300
	v_add_u32_e32 v100, 16, v16
	v_mad_i64_i32 v[100:101], s[12:13], v100, s14, v[14:15]
	global_load_dwordx4 v[100:103], v[100:101], off nt
	v_add_u32_e32 v104, 32, v16
	v_mad_i64_i32 v[104:105], s[12:13], v104, s14, v[14:15]
	global_load_dwordx4 v[104:107], v[104:105], off nt
	v_add_u32_e32 v108, 48, v16
	v_mad_i64_i32 v[108:109], s[12:13], v108, s14, v[14:15]
	global_load_dwordx4 v[108:111], v[108:109], off nt
	v_add_u32_e32 v14, 0x400, v9
	v_add_u32_e32 v16, 0x800, v9
	s_barrier
	s_waitcnt vmcnt(3)
	ds_write2_b32 v4, v10, v11 offset1:1
	ds_write2_b32 v4, v12, v13 offset0:2 offset1:3
	s_waitcnt vmcnt(2)
	ds_write2_b32 v5, v100, v101 offset1:1
	ds_write2_b32 v5, v102, v103 offset0:2 offset1:3
	s_waitcnt vmcnt(1)
	ds_write2_b32 v6, v104, v105 offset1:1
	ds_write2_b32 v6, v106, v107 offset0:2 offset1:3
	s_waitcnt vmcnt(0)
	ds_write2_b32 v7, v108, v109 offset1:1
	ds_write2_b32 v7, v110, v111 offset0:2 offset1:3
	s_waitcnt lgkmcnt(0)
	s_barrier
	ds_read2_b32 v[10:11], v8 offset1:130
	ds_read2_b32 v[12:13], v9 offset0:65 offset1:195
	ds_read2_b32 v[14:15], v14 offset0:69 offset1:199
	ds_read2_b32 v[16:17], v16 offset0:73 offset1:203
	ds_read2_b32 v[18:19], v18 offset0:77 offset1:207
	s_waitcnt lgkmcnt(3)
	v_cvt_pk_bf16_f32 v10, v10, v12
	v_add_u32_e32 v12, 0x400, v8
	v_cvt_pk_bf16_f32 v11, v11, v13
	ds_read2_b32 v[12:13], v12 offset0:4 offset1:134
	s_waitcnt lgkmcnt(0)
	v_cvt_pk_bf16_f32 v12, v12, v14
	v_add_u32_e32 v14, 0x800, v8
	v_cvt_pk_bf16_f32 v13, v13, v15
	ds_read2_b32 v[14:15], v14 offset0:8 offset1:138
	s_waitcnt lgkmcnt(0)
	v_cvt_pk_bf16_f32 v14, v14, v16
	v_add_u32_e32 v16, 0xc00, v8
	v_cvt_pk_bf16_f32 v15, v15, v17
	ds_read2_b32 v[16:17], v16 offset0:12 offset1:142
	s_waitcnt lgkmcnt(0)
	v_cvt_pk_bf16_f32 v16, v16, v18
	v_add_u32_e32 v18, s6, v3
	v_cvt_pk_bf16_f32 v17, v17, v19
	v_ashrrev_i32_e32 v19, 31, v18
	v_lshlrev_b64 v[18:19], 11, v[18:19]
	v_lshl_add_u64 v[18:19], s[0:1], 0, v[18:19]
	v_lshl_add_u64 v[18:19], s[2:3], 1, v[18:19]
	v_lshl_add_u64 v[18:19], v[18:19], 0, v[128:129]
	global_store_dwordx4 v[18:19], v[10:13], off
	global_store_dwordx4 v[18:19], v[14:17], off offset:16
	s_cbranch_scc1 .LBB0_2407

.LBB0_2412:
	s_ashr_i32 s2, s8, 31
	s_lshr_b32 s2, s2, 28
	s_add_i32 s2, s8, s2
	s_ashr_i32 s3, s2, 4
	s_lshl_b32 s2, s3, 10
	s_sub_i32 s2, s10, s2
	s_lshl_b32 s6, s3, 6
	v_add_u32_e32 v16, s2, v2
	s_ashr_i32 s7, s6, 31
	v_ashrrev_i32_e32 v17, 31, v16
	v_lshl_add_u64 v[14:15], s[6:7], 2, v[0:1]
	v_lshlrev_b64 v[10:11], 12, v[16:17]
	v_lshl_add_u64 v[10:11], v[14:15], 0, v[10:11]
	global_load_dwordx4 v[10:13], v[10:11], off nt
	v_add_u32_e32 v18, 0xc00, v9
	s_ashr_i32 s3, s2, 31
	s_add_i32 s8, s8, s9
	s_add_i32 s10, s10, s11
	s_cmpk_gt_i32 s8, 0xff
	v_add_u32_e32 v100, 16, v16
	v_ashrrev_i32_e32 v101, 31, v100
	v_lshlrev_b64 v[100:101], 12, v[100:101]
	v_lshl_add_u64 v[100:101], v[14:15], 0, v[100:101]
	global_load_dwordx4 v[100:103], v[100:101], off nt
	v_add_u32_e32 v104, 32, v16
	v_ashrrev_i32_e32 v105, 31, v104
	v_lshlrev_b64 v[104:105], 12, v[104:105]
	v_lshl_add_u64 v[104:105], v[14:15], 0, v[104:105]
	global_load_dwordx4 v[104:107], v[104:105], off nt
	v_add_u32_e32 v108, 48, v16
	v_ashrrev_i32_e32 v109, 31, v108
	v_lshlrev_b64 v[108:109], 12, v[108:109]
	v_lshl_add_u64 v[108:109], v[14:15], 0, v[108:109]
	global_load_dwordx4 v[108:111], v[108:109], off nt
	v_add_u32_e32 v14, 0x400, v9
	v_add_u32_e32 v16, 0x800, v9
	s_barrier
	s_waitcnt vmcnt(3)
	ds_write2_b32 v4, v10, v11 offset1:1
	ds_write2_b32 v4, v12, v13 offset0:2 offset1:3
	s_waitcnt vmcnt(2)
	ds_write2_b32 v5, v100, v101 offset1:1
	ds_write2_b32 v5, v102, v103 offset0:2 offset1:3
	s_waitcnt vmcnt(1)
	ds_write2_b32 v6, v104, v105 offset1:1
	ds_write2_b32 v6, v106, v107 offset0:2 offset1:3
	s_waitcnt vmcnt(0)
	ds_write2_b32 v7, v108, v109 offset1:1
	ds_write2_b32 v7, v110, v111 offset0:2 offset1:3
	s_waitcnt lgkmcnt(0)
	s_barrier
	ds_read2_b32 v[10:11], v8 offset1:130
	ds_read2_b32 v[12:13], v9 offset0:65 offset1:195
	ds_read2_b32 v[14:15], v14 offset0:69 offset1:199
	ds_read2_b32 v[16:17], v16 offset0:73 offset1:203
	ds_read2_b32 v[18:19], v18 offset0:77 offset1:207
	s_waitcnt lgkmcnt(3)
	v_cvt_pk_bf16_f32 v10, v10, v12
	v_add_u32_e32 v12, 0x400, v8
	v_cvt_pk_bf16_f32 v11, v11, v13
	ds_read2_b32 v[12:13], v12 offset0:4 offset1:134
	s_waitcnt lgkmcnt(0)
	v_cvt_pk_bf16_f32 v12, v12, v14
	v_add_u32_e32 v14, 0x800, v8
	v_cvt_pk_bf16_f32 v13, v13, v15
	ds_read2_b32 v[14:15], v14 offset0:8 offset1:138
	s_waitcnt lgkmcnt(0)
	v_cvt_pk_bf16_f32 v14, v14, v16
	v_add_u32_e32 v16, 0xc00, v8
	v_cvt_pk_bf16_f32 v15, v15, v17
	ds_read2_b32 v[16:17], v16 offset0:12 offset1:142
	s_waitcnt lgkmcnt(0)
	v_cvt_pk_bf16_f32 v16, v16, v18
	v_add_u32_e32 v18, s6, v3
	v_cvt_pk_bf16_f32 v17, v17, v19
	v_ashrrev_i32_e32 v19, 31, v18
	v_lshlrev_b64 v[18:19], 11, v[18:19]
	v_lshl_add_u64 v[18:19], s[0:1], 0, v[18:19]
	v_lshl_add_u64 v[18:19], s[2:3], 1, v[18:19]
	v_lshl_add_u64 v[18:19], v[18:19], 0, v[128:129]
	global_store_dwordx4 v[18:19], v[10:13], off
	global_store_dwordx4 v[18:19], v[14:17], off offset:16
	s_cbranch_scc0 .LBB0_2412

.LBB0_2419:
	s_ashr_i32 s2, s8, 31
	s_lshr_b32 s2, s2, 28
	s_add_i32 s2, s8, s2
	s_ashr_i32 s3, s2, 4
	s_lshl_b32 s2, s3, 10
	s_lshl_b32 s6, s3, 6
	s_sub_i32 s2, s10, s2
	s_ashr_i32 s7, s6, 31
	v_lshl_add_u64 v[14:15], s[6:7], 2, v[0:1]
	v_add_u32_e32 v16, s2, v2
	v_mad_i64_i32 v[10:11], s[12:13], v16, s14, v[14:15]
	global_load_dwordx4 v[10:13], v[10:11], off nt
	v_add_u32_e32 v18, 0xc00, v9
	s_ashr_i32 s3, s2, 31
	s_add_i32 s8, s8, s9
	s_add_i32 s10, s10, s11
	s_cmpk_lt_i32 s8, 0x610
	v_add_u32_e32 v100, 16, v16
	v_mad_i64_i32 v[100:101], s[12:13], v100, s14, v[14:15]
	global_load_dwordx4 v[100:103], v[100:101], off nt
	v_add_u32_e32 v104, 32, v16
	v_mad_i64_i32 v[104:105], s[12:13], v104, s14, v[14:15]
	global_load_dwordx4 v[104:107], v[104:105], off nt
	v_add_u32_e32 v108, 48, v16
	v_mad_i64_i32 v[108:109], s[12:13], v108, s14, v[14:15]
	global_load_dwordx4 v[108:111], v[108:109], off nt
	v_add_u32_e32 v14, 0x400, v9
	v_add_u32_e32 v16, 0x800, v9
	s_barrier
	s_waitcnt vmcnt(3)
	ds_write2_b32 v4, v10, v11 offset1:1
	ds_write2_b32 v4, v12, v13 offset0:2 offset1:3
	s_waitcnt vmcnt(2)
	ds_write2_b32 v5, v100, v101 offset1:1
	ds_write2_b32 v5, v102, v103 offset0:2 offset1:3
	s_waitcnt vmcnt(1)
	ds_write2_b32 v6, v104, v105 offset1:1
	ds_write2_b32 v6, v106, v107 offset0:2 offset1:3
	s_waitcnt vmcnt(0)
	ds_write2_b32 v7, v108, v109 offset1:1
	ds_write2_b32 v7, v110, v111 offset0:2 offset1:3
	s_waitcnt lgkmcnt(0)
	s_barrier
	ds_read2_b32 v[10:11], v8 offset1:130
	ds_read2_b32 v[12:13], v9 offset0:65 offset1:195
	ds_read2_b32 v[14:15], v14 offset0:69 offset1:199
	ds_read2_b32 v[16:17], v16 offset0:73 offset1:203
	ds_read2_b32 v[18:19], v18 offset0:77 offset1:207
	s_waitcnt lgkmcnt(3)
	v_cvt_pk_bf16_f32 v10, v10, v12
	v_add_u32_e32 v12, 0x400, v8
	v_cvt_pk_bf16_f32 v11, v11, v13
	ds_read2_b32 v[12:13], v12 offset0:4 offset1:134
	s_waitcnt lgkmcnt(0)
	v_cvt_pk_bf16_f32 v12, v12, v14
	v_add_u32_e32 v14, 0x800, v8
	v_cvt_pk_bf16_f32 v13, v13, v15
	ds_read2_b32 v[14:15], v14 offset0:8 offset1:138
	s_waitcnt lgkmcnt(0)
	v_cvt_pk_bf16_f32 v14, v14, v16
	v_add_u32_e32 v16, 0xc00, v8
	v_cvt_pk_bf16_f32 v15, v15, v17
	ds_read2_b32 v[16:17], v16 offset0:12 offset1:142
	s_waitcnt lgkmcnt(0)
	v_cvt_pk_bf16_f32 v16, v16, v18
	v_add_u32_e32 v18, s6, v3
	v_cvt_pk_bf16_f32 v17, v17, v19
	v_ashrrev_i32_e32 v19, 31, v18
	v_lshlrev_b64 v[18:19], 11, v[18:19]
	v_lshl_add_u64 v[18:19], s[0:1], 0, v[18:19]
	v_lshl_add_u64 v[18:19], s[2:3], 1, v[18:19]
	v_lshl_add_u64 v[18:19], v[18:19], 0, v[128:129]
	global_store_dwordx4 v[18:19], v[10:13], off
	global_store_dwordx4 v[18:19], v[14:17], off offset:16
	s_cbranch_scc1 .LBB0_2419
